# grid barrier: non-leader workgroups wait on the global release generation directly instead of the per-XCD relay counter (one fewer polling hop per barrier)
# speedup vs baseline: 1.0028x; 1.0028x over previous
; __device__ __forceinline__ unsigned xb_ld(unsigned* p)              { return __hip_atomic_load(p, __ATOMIC_RELAXED, __HIP_MEMORY_SCOPE_AGENT); }
; __device__ __forceinline__ unsigned xb_add(unsigned* p, unsigned v) { return __hip_atomic_fetch_add(p, v, __ATOMIC_RELAXED, __HIP_MEMORY_SCOPE_AGENT); }
; #define XB_SPIN(cond, bar) do { unsigned _sp = 0; while (cond) { __builtin_amdgcn_s_sleep(1); \
;     if ((++_sp & 255u) == 0u) { if (xb_ld(&(bar)[XB_TMO])) break; if (_sp > XB_SPIN_CAP) { atomicAdd(&(bar)[XB_TMO], 1u); break; } } } } while (0)
; __device__ __forceinline__ void xcd_barrier(const XcdBarrier& b) {
;     ...
;         const unsigned old = xb_add(&bar[XB_XSUB(b.x)], 1u);
;         const unsigned gen = old / nloc;
;         if (old + 1u == (gen + 1u) * nloc) {
;             __builtin_amdgcn_fence(__ATOMIC_RELEASE, "agent");
;             asm volatile("s_waitcnt vmcnt(0)" ::: "memory");
;             const unsigned og = xb_add(&bar[XB_TOP], 1u);
;             const unsigned tg = og / nx;
;             if (og + 1u == (tg + 1u) * nx) xb_add(&bar[XB_TOPGEN], 1u);
;             else XB_SPIN(xb_ld(&bar[XB_TOPGEN]) == tg, bar);
;             __builtin_amdgcn_fence(__ATOMIC_ACQUIRE, "agent");
;             xb_add(&bar[XB_XGEN(b.x)], 1u);
;             asm volatile("s_waitcnt vmcnt(0)" ::: "memory");
;         } else {
;             XB_SPIN(xb_ld(&bar[XB_XGEN(b.x)]) == gen, bar);
.LBB0_143:
	s_or_b64 exec, exec, s[4:5]
	v_cvt_f32_u32_e32 v5, v3
	s_waitcnt vmcnt(0)
	v_readfirstlane_b32 s4, v4
	v_sub_u32_e32 v4, 0, v3
	v_rcp_iflag_f32_e32 v5, v5
	v_add_u32_e32 v6, s4, v1
	v_mul_f32_e32 v5, 0x4f7ffffe, v5
	v_cvt_u32_f32_e32 v5, v5
	v_mul_lo_u32 v1, v4, v5
	v_mul_hi_u32 v1, v5, v1
	v_add_u32_e32 v1, v5, v1
	v_mul_hi_u32 v1, v6, v1
	v_mul_lo_u32 v4, v1, v3
	v_sub_u32_e32 v4, v6, v4
	v_add_u32_e32 v5, 1, v1
	v_cmp_ge_u32_e32 vcc, v4, v3
	s_nop 1
	v_cndmask_b32_e32 v1, v1, v5, vcc
	v_sub_u32_e32 v5, v4, v3
	v_cndmask_b32_e32 v4, v4, v5, vcc
	v_add_u32_e32 v5, 1, v1
	v_cmp_ge_u32_e32 vcc, v4, v3
	v_add_u32_e32 v4, 1, v6
	s_nop 0
	v_cndmask_b32_e32 v1, v1, v5, vcc
	v_mul_lo_u32 v5, v3, v1
	v_add_u32_e32 v3, v5, v3
	v_cmp_ne_u32_e32 vcc, v4, v3
	s_and_saveexec_b64 s[4:5], vcc
	s_xor_b64 s[4:5], exec, s[4:5]
	s_cbranch_execz .LBB0_157
	v_readlane_b32 s6, v253, 26
	v_readlane_b32 s7, v253, 27
	s_waitcnt lgkmcnt(0)
	s_nop 3
	global_load_dword v2, v0, s[6:7] sc1
	s_waitcnt vmcnt(0)
	v_cmp_eq_u32_e32 vcc, v2, v1
	s_and_saveexec_b64 s[22:23], vcc
	s_cbranch_execz .LBB0_156
	s_mov_b32 s6, 1
	s_mov_b64 s[24:25], 0
	s_branch .LBB0_147

; __device__ __forceinline__ unsigned xb_ld(unsigned* p)              { return __hip_atomic_load(p, __ATOMIC_RELAXED, __HIP_MEMORY_SCOPE_AGENT); }
; __device__ __forceinline__ unsigned xb_add(unsigned* p, unsigned v) { return __hip_atomic_fetch_add(p, v, __ATOMIC_RELAXED, __HIP_MEMORY_SCOPE_AGENT); }
; #define XB_SPIN(cond, bar) do { unsigned _sp = 0; while (cond) { __builtin_amdgcn_s_sleep(1); \
;     if ((++_sp & 255u) == 0u) { if (xb_ld(&(bar)[XB_TMO])) break; if (_sp > XB_SPIN_CAP) { atomicAdd(&(bar)[XB_TMO], 1u); break; } } } } while (0)
; __device__ __forceinline__ void xcd_barrier(const XcdBarrier& b) {
;     ...
;         const unsigned old = xb_add(&bar[XB_XSUB(b.x)], 1u);
;         const unsigned gen = old / nloc;
;         if (old + 1u == (gen + 1u) * nloc) {
;             __builtin_amdgcn_fence(__ATOMIC_RELEASE, "agent");
;             asm volatile("s_waitcnt vmcnt(0)" ::: "memory");
;             const unsigned og = xb_add(&bar[XB_TOP], 1u);
;             const unsigned tg = og / nx;
;             if (og + 1u == (tg + 1u) * nx) xb_add(&bar[XB_TOPGEN], 1u);
;             else XB_SPIN(xb_ld(&bar[XB_TOPGEN]) == tg, bar);
;             __builtin_amdgcn_fence(__ATOMIC_ACQUIRE, "agent");
;             xb_add(&bar[XB_XGEN(b.x)], 1u);
;             asm volatile("s_waitcnt vmcnt(0)" ::: "memory");
;         } else {
;             XB_SPIN(xb_ld(&bar[XB_XGEN(b.x)]) == gen, bar);
.LBB0_1117:
	s_or_b64 exec, exec, s[4:5]
	v_cvt_f32_u32_e32 v5, v3
	s_waitcnt vmcnt(0)
	v_readfirstlane_b32 s4, v4
	v_sub_u32_e32 v4, 0, v3
	v_rcp_iflag_f32_e32 v5, v5
	v_add_u32_e32 v6, s4, v1
	v_mul_f32_e32 v5, 0x4f7ffffe, v5
	v_cvt_u32_f32_e32 v5, v5
	v_mul_lo_u32 v1, v4, v5
	v_mul_hi_u32 v1, v5, v1
	v_add_u32_e32 v1, v5, v1
	v_mul_hi_u32 v1, v6, v1
	v_mul_lo_u32 v4, v1, v3
	v_sub_u32_e32 v4, v6, v4
	v_add_u32_e32 v5, 1, v1
	v_cmp_ge_u32_e32 vcc, v4, v3
	s_nop 1
	v_cndmask_b32_e32 v1, v1, v5, vcc
	v_sub_u32_e32 v5, v4, v3
	v_cndmask_b32_e32 v4, v4, v5, vcc
	v_add_u32_e32 v5, 1, v1
	v_cmp_ge_u32_e32 vcc, v4, v3
	v_add_u32_e32 v4, 1, v6
	s_nop 0
	v_cndmask_b32_e32 v1, v1, v5, vcc
	v_mul_lo_u32 v5, v3, v1
	v_add_u32_e32 v3, v5, v3
	v_cmp_ne_u32_e32 vcc, v4, v3
	s_and_saveexec_b64 s[4:5], vcc
	s_xor_b64 s[4:5], exec, s[4:5]
	s_cbranch_execz .LBB0_1131
	v_readlane_b32 s22, v253, 26
	v_readlane_b32 s23, v253, 27
	s_waitcnt lgkmcnt(0)
	s_nop 3
	global_load_dword v2, v0, s[22:23] sc1
	s_waitcnt vmcnt(0)
	v_cmp_eq_u32_e32 vcc, v2, v1
	s_and_saveexec_b64 s[22:23], vcc
	s_cbranch_execz .LBB0_1130
	s_mov_b32 s12, 1
	s_mov_b64 s[24:25], 0
	s_branch .LBB0_1121

; __device__ __forceinline__ unsigned xb_ld(unsigned* p)              { return __hip_atomic_load(p, __ATOMIC_RELAXED, __HIP_MEMORY_SCOPE_AGENT); }
; __device__ __forceinline__ unsigned xb_add(unsigned* p, unsigned v) { return __hip_atomic_fetch_add(p, v, __ATOMIC_RELAXED, __HIP_MEMORY_SCOPE_AGENT); }
; #define XB_SPIN(cond, bar) do { unsigned _sp = 0; while (cond) { __builtin_amdgcn_s_sleep(1); \
;     if ((++_sp & 255u) == 0u) { if (xb_ld(&(bar)[XB_TMO])) break; if (_sp > XB_SPIN_CAP) { atomicAdd(&(bar)[XB_TMO], 1u); break; } } } } while (0)
; __device__ __forceinline__ void xcd_barrier(const XcdBarrier& b) {
;     ...
;         const unsigned old = xb_add(&bar[XB_XSUB(b.x)], 1u);
;         const unsigned gen = old / nloc;
;         if (old + 1u == (gen + 1u) * nloc) {
;             __builtin_amdgcn_fence(__ATOMIC_RELEASE, "agent");
;             asm volatile("s_waitcnt vmcnt(0)" ::: "memory");
;             const unsigned og = xb_add(&bar[XB_TOP], 1u);
;             const unsigned tg = og / nx;
;             if (og + 1u == (tg + 1u) * nx) xb_add(&bar[XB_TOPGEN], 1u);
;             else XB_SPIN(xb_ld(&bar[XB_TOPGEN]) == tg, bar);
;             __builtin_amdgcn_fence(__ATOMIC_ACQUIRE, "agent");
;             xb_add(&bar[XB_XGEN(b.x)], 1u);
;             asm volatile("s_waitcnt vmcnt(0)" ::: "memory");
;         } else {
;             XB_SPIN(xb_ld(&bar[XB_XGEN(b.x)]) == gen, bar);
.LBB0_1387:
	s_or_b64 exec, exec, s[4:5]
	v_cvt_f32_u32_e32 v5, v3
	s_waitcnt vmcnt(0)
	v_readfirstlane_b32 s4, v4
	v_sub_u32_e32 v4, 0, v3
	v_rcp_iflag_f32_e32 v5, v5
	v_add_u32_e32 v6, s4, v1
	v_mul_f32_e32 v5, 0x4f7ffffe, v5
	v_cvt_u32_f32_e32 v5, v5
	v_mul_lo_u32 v1, v4, v5
	v_mul_hi_u32 v1, v5, v1
	v_add_u32_e32 v1, v5, v1
	v_mul_hi_u32 v1, v6, v1
	v_mul_lo_u32 v4, v1, v3
	v_sub_u32_e32 v4, v6, v4
	v_add_u32_e32 v5, 1, v1
	v_cmp_ge_u32_e32 vcc, v4, v3
	s_nop 1
	v_cndmask_b32_e32 v1, v1, v5, vcc
	v_sub_u32_e32 v5, v4, v3
	v_cndmask_b32_e32 v4, v4, v5, vcc
	v_add_u32_e32 v5, 1, v1
	v_cmp_ge_u32_e32 vcc, v4, v3
	v_add_u32_e32 v4, 1, v6
	s_nop 0
	v_cndmask_b32_e32 v1, v1, v5, vcc
	v_mul_lo_u32 v5, v3, v1
	v_add_u32_e32 v3, v5, v3
	v_cmp_ne_u32_e32 vcc, v4, v3
	s_and_saveexec_b64 s[4:5], vcc
	s_xor_b64 s[4:5], exec, s[4:5]
	s_cbranch_execz .LBB0_1401
	v_readlane_b32 s6, v253, 26
	v_readlane_b32 s7, v253, 27
	s_waitcnt lgkmcnt(0)
	s_nop 3
	global_load_dword v2, v0, s[6:7] sc1
	s_waitcnt vmcnt(0)
	v_cmp_eq_u32_e32 vcc, v2, v1
	s_and_saveexec_b64 s[6:7], vcc
	s_cbranch_execz .LBB0_1400
	s_mov_b32 s12, 1
	s_mov_b64 s[22:23], 0
	s_branch .LBB0_1391
